# arrival flag stored first thing in the seam's thread-0 path (before the LDS reads)
# speedup vs baseline: 1.0184x; 1.0024x over previous
.Lxb_noinv:
	s_or_b64 exec, exec, s[4:5]
	v_cmp_eq_u32_e32 vcc, 0, v210
	s_and_saveexec_b64 s[4:5], vcc
	s_cbranch_execz .LBB0_463
	v_readlane_b32 s6, v240, 5
	v_readlane_b32 s7, v240, 6
	v_readlane_b32 s8, v240, 0
	s_add_i32 s101, s101, 1
	v_mov_b32_e32 v2, s101
	s_and_b32 s9, s8, 7
	s_lshl_b32 s9, s9, 8
	s_add_u32 s9, s9, 0x12000
	s_add_u32 s12, s6, s9
	s_addc_u32 s13, s7, 0
	s_lshr_b32 s9, s8, 3
	s_lshl_b32 s9, s9, 2
	v_mov_b32_e32 v3, s9
	global_store_dword v3, v2, s[12:13]
	v_readlane_b32 s6, v240, 60
	s_and_b32 s3, s3, 15
	s_lshl_b32 s3, s3, 8
	v_mov_b32_e32 v0, s6
	ds_read_b64 v[0:1], v0
	v_readlane_b32 s6, v240, 5
	v_readlane_b32 s7, v240, 6
	s_waitcnt lgkmcnt(0)
	v_cmp_ne_u32_e32 vcc, 0, v0
	s_cbranch_vccnz .Lxb_have
	s_mov_b32 s12, 0

.Lxb_have:
	v_readfirstlane_b32 s10, v0
	v_readfirstlane_b32 s11, v1
	v_readlane_b32 s8, v240, 60
	v_mov_b32_e32 v2, 1
	s_nop 1
	v_mov_b32_e32 v4, s8
	ds_read_b32 v4, v4 offset:8
	v_readlane_b32 s8, v240, 0
	s_nop 0
	s_lshl_b32 s9, s8, 6
	s_add_u32 s9, s9, 0x4000
	s_add_u32 s14, s6, s9
	s_addc_u32 s15, s7, 0
	s_waitcnt lgkmcnt(0)
	v_readfirstlane_b32 s9, v4
	s_cmp_eq_u32 s9, 1
	s_cbranch_scc0 .Lxb_grid
	s_mov_b32 s9, 0x3cfdf3f4
	s_bitcmp1_b32 s9, s70
	s_cbranch_scc0 .Lxb_grid
	s_and_b32 s9, s8, 7
	s_lshl_b32 s9, s9, 8
	s_add_u32 s9, s9, 0x12000
	s_add_u32 s12, s6, s9
	s_addc_u32 s13, s7, 0
	s_lshr_b32 s9, s8, 3
	s_lshl_b32 s9, s9, 2
	s_bfe_u32 s9, s8, 0x20003
	s_lshl_b32 s9, s9, 2
	s_mov_b32 exec_lo, 0xff
	s_mov_b32 exec_hi, 0
	v_mbcnt_lo_u32_b32 v3, -1, 0
	v_lshlrev_b32_e32 v3, 4, v3
	v_add_u32_e32 v3, s9, v3
	s_mov_b32 s9, 0
